# static s_setprio 1 for waves 4-7 only in the two block-cooperative attention phases (sub-phases 3,4), back to 0 before dil_merge; phase-repeat probe showed the raise slowed the wave-private dilated ph
# speedup vs baseline: 1.0041x; 1.0041x over previous
; __global__ void __launch_bounds__(NTHREADS) fwd_kernel(Params p, int ph0, int ph1) {
;     ...
;   for (int pi = ph0; pi < ph1; ++pi) {
;     int ph = pi, rep = 0;
;     if (N_PROBE > 0 && pi >= N_PHASES) { ph = (pi == N_PHASES) ? PROBE_A : PROBE_B; rep = 1; }
;     int tid;
;     asm volatile("v_mbcnt_lo_u32_b32 %0, -1, 0\n\tv_mbcnt_hi_u32_b32 %0, -1, %0\n\tv_lshl_add_u32 %0, %1, 6, %0" : "=&v"(tid) : "s"(widx));
;     int bid_ = blockIdx.x, nb_ = gridDim.x;
;     asm volatile("" : "+s"(bid_), "+s"(nb_));
;     run_phase(p, ph, tid, rep, bid_, nb_);
.LBB0_19:
	v_readlane_b32 s0, v254, 32
	v_readlane_b32 s1, v254, 33
	v_mbcnt_lo_u32_b32 v239, -1, 0
	v_mbcnt_hi_u32_b32 v239, -1, v239
	v_lshl_add_u32 v239, s34, 6, v239
	s_setprio 0
	s_cmp_lt_u32 s34, 4
	s_cbranch_scc1 .Lprio_done
	s_bitcmp1_b32 0x6018, s48
	s_cbranch_scc0 .Lprio_done
	s_setprio 1

; DI void dil_merge(const Params& p, int gw, int nw, int lane) {
;   const u16* og = (const u16*)(p.ws + OFF_OG);
;   const float* lse = (const float*)(p.ws + OFF_LSE);
;   u16* ya = (u16*)(p.ws + OFF_YA);
;   const int hh = lane >> 4, d0 = (lane & 15) * 8;
;   for (int tok = gw; tok < T_; tok += nw) {
;     const float l0 = lse[((size_t)0 * T_ + tok) * 4 + hh], l1 = lse[((size_t)1 * T_ + tok) * 4 + hh], l2 = lse[((size_t)2 * T_ + tok) * 4 + hh];
;     const float mx = fmaxf(l0, fmaxf(l1, l2));
;     float w0 = __expf(l0 - mx), w1 = __expf(l1 - mx), w2 = __expf(l2 - mx);
;     const float inv = 1.f / (w0 + w1 + w2);
;     w0 *= inv; w1 *= inv; w2 *= inv;
;     const uint4 a0 = *reinterpret_cast<const uint4*>(og + ((size_t)0 * T_ + tok) * 512 + hh * 128 + d0);
;     const uint4 a1 = *reinterpret_cast<const uint4*>(og + ((size_t)1 * T_ + tok) * 512 + hh * 128 + d0);
;     const uint4 a2 = *reinterpret_cast<const uint4*>(og + ((size_t)2 * T_ + tok) * 512 + hh * 128 + d0);
.LBB0_230:
	s_setprio 0
	s_movk_i32 s0, 0x4000
	v_cmp_gt_i32_e32 vcc, s0, v178
	s_and_saveexec_b64 s[0:1], vcc
	s_cbranch_execz .LBB0_233
	v_and_b32_e32 v0, 63, v239
	v_lshrrev_b32_e32 v0, 4, v0
	v_ashrrev_i32_e32 v179, 31, v178
	s_waitcnt vmcnt(0)
	v_and_b32_e32 v5, 15, v239
	v_lshlrev_b64 v[2:3], 10, v[178:179]
	v_lshlrev_b32_e32 v4, 8, v0
	v_lshlrev_b32_e32 v5, 4, v5
	v_or3_b32 v2, v2, v4, v5
	s_ashr_i32 s85, s84, 31
	v_lshlrev_b64 v[4:5], 4, v[178:179]
	s_lshl_b64 s[4:5], s[84:85], 10
	v_lshl_or_b32 v4, v0, 2, v4
	s_lshl_b64 s[6:7], s[84:85], 4
	s_mov_b64 s[8:9], 0
	v_mov_b32_e32 v0, v178
	v_lshl_add_u64 v[6:7], s[74:75], 0, v[4:5]
	v_add_co_u32_e32 v8, vcc, 0x2b920000, v6
	s_nop 1
	v_addc_co_u32_e32 v9, vcc, 0, v7, vcc
	global_load_dword v10, v[8:9], off
	v_add_co_u32_e32 v8, vcc, 0x2b960000, v6
	s_nop 1
	v_addc_co_u32_e32 v9, vcc, 0, v7, vcc
	global_load_dword v11, v[8:9], off
	v_add_co_u32_e32 v8, vcc, 0x2b9a0000, v6
	s_nop 1
	v_addc_co_u32_e32 v9, vcc, 0, v7, vcc
	global_load_dword v12, v[8:9], off
	v_lshl_add_u64 v[24:25], s[74:75], 0, v[2:3]
	v_add_co_u32_e32 v6, vcc, 0x28920000, v24
	s_nop 1
	v_addc_co_u32_e32 v7, vcc, 0, v25, vcc
	global_load_dwordx4 v[32:35], v[6:7], off
	v_add_co_u32_e32 v6, vcc, 0x29920000, v24
	s_nop 1
	v_addc_co_u32_e32 v7, vcc, 0, v25, vcc
	global_load_dwordx4 v[36:39], v[6:7], off
	v_add_co_u32_e32 v6, vcc, 0x2a920000, v24
	s_nop 1
	v_addc_co_u32_e32 v7, vcc, 0, v25, vcc
	global_load_dwordx4 v[40:43], v[6:7], off
